# layer-1 Wout conversion also moved into layer-0 FFN2's idle workgroups (waves 640..767 of the 96 idle WGs); P1(l1) skips tiles 352..1183; layer-0 routines dropped
# baseline (speedup 1.0000x reference)
; #define WT_LOAD() do { _Pragma("unroll") for (int i = 0; i < 16; ++i) rg[i] = sp ? sp[(size_t)(k0 + kq + i * 8) * ld] : 0.f; } while (0)
; __device__ __forceinline__ void phase_weights(int wv, const Params& p, int l, LAS unsigned char* lds, int first, int stride) {
;     ...
;     if (ti < 1536) { WT_DECODE(ti); WT_LOAD(); }
;     while (ti < 1536) {
;         bf16_t* cdst = dst + (size_t)n0 * K + k0; const int cK = K;
;         __syncthreads();
; #pragma unroll
;         for (int i = 0; i < 16; ++i) tile[(kq + i * 8) * 65 + nl] = rg[i];
;         ti += stride;
;         if (ti < 1536) { WT_DECODE(ti); WT_LOAD(); }
.Lws_loop:
	s_cmpk_lt_i32 s46, 0x160
	s_cbranch_scc1 .Lws_done
	s_cmpk_gt_i32 s46, 0x49f
	s_cbranch_scc1 .Lws_done
	s_add_i32 s46, s46, s1
	s_add_i32 s42, s42, s43
	s_branch .Lws_loop

; __device__ __forceinline__ unsigned pk_bf16(float lo, float hi) { unsigned r; asm volatile("v_cvt_pk_bf16_f32 %0, %1, %2" : "=v"(r) : "v"(lo), "v"(hi)); return r; }
; #define WT_LOAD() do { _Pragma("unroll") for (int i = 0; i < 16; ++i) rg[i] = sp ? sp[(size_t)(k0 + kq + i * 8) * ld] : 0.f; } while (0)
; __device__ __forceinline__ void phase_weights(int wv, const Params& p, int l, LAS unsigned char* lds, int first, int stride) {
;     ...
;     if (ti < 1536) { WT_DECODE(ti); WT_LOAD(); }
;     while (ti < 1536) {
;         bf16_t* cdst = dst + (size_t)n0 * K + k0; const int cK = K;
;         __syncthreads();
; #pragma unroll
;         for (int i = 0; i < 16; ++i) tile[(kq + i * 8) * 65 + nl] = rg[i];
;         ti += stride;
;         if (ti < 1536) { WT_DECODE(ti); WT_LOAD(); }
;         __syncthreads();
;         { const int nn = tid >> 3, ks = tid & 7; float v[16];
; #pragma unroll
;             for (int j = 0; j < 16; ++j) v[j] = tile[(ks * 16 + j) * 65 + nn];
;             u32x4 w0, w1; w0.x = pk_bf16(v[0], v[1]); w0.y = pk_bf16(v[2], v[3]); w0.z = pk_bf16(v[4], v[5]); w0.w = pk_bf16(v[6], v[7]);
;             w1.x = pk_bf16(v[8], v[9]); w1.y = pk_bf16(v[10], v[11]); w1.z = pk_bf16(v[12], v[13]); w1.w = pk_bf16(v[14], v[15]);
;             bf16_t* o = cdst + (size_t)nn * cK + ks * 16; *(u32x4*)o = w0; *(u32x4*)(o + 8) = w1; }
.LBB0_1505:
	v_readlane_b32 s24, v255, 3
	s_cmpk_lt_u32 s24, 160
	s_cbranch_scc1 .Lew_end_b
	s_cmpk_lg_u32 s44, 0x100
	s_cbranch_scc1 .Lew_end_b
	s_load_dwordx2 s[8:9], s[90:91], 0x88
	s_load_dwordx2 s[10:11], s[90:91], 0x90
	s_load_dwordx2 s[12:13], s[90:91], 0xa8
	v_mbcnt_lo_u32_b32 v2, -1, 0
	v_mbcnt_hi_u32_b32 v2, -1, v2
	v_and_b32_e32 v3, 15, v2
	v_lshrrev_b32_e32 v6, 5, v2
	v_lshlrev_b32_e32 v7, 4, v3
	v_mul_u32_u24_e32 v8, 0x2c000, v6
	v_add_u32_e32 v12, v7, v8
	v_add_u32_e32 v12, 0xb00000, v12
	v_mov_b32_e32 v13, 0
	v_and_b32_e32 v8, 16, v2
	v_cmp_ne_u32_e32 vcc, 0, v8
	s_waitcnt lgkmcnt(0)
	v_mov_b32_e32 v4, s8
	v_mov_b32_e32 v5, s9
	v_mov_b32_e32 v8, s10
	v_mov_b32_e32 v9, s11
	s_nop 1
	v_cndmask_b32_e32 v4, v4, v8, vcc
	v_cndmask_b32_e32 v5, v5, v9, vcc
	v_lshl_add_u64 v[4:5], v[4:5], 0, v[12:13]
	v_and_b32_e32 v8, 1, v3
	v_lshlrev_b32_e32 v10, 7, v8
	v_bfe_u32 v8, v3, 1, 2
	v_lshl_add_u32 v10, v8, 2, v10
	v_lshrrev_b32_e32 v8, 3, v3
	v_lshl_add_u32 v10, v8, 5, v10
	v_bfe_u32 v8, v2, 4, 1
	v_lshl_add_u32 v10, v8, 4, v10
	v_add_u32_e32 v10, 2, v10
	v_lshlrev_b32_e32 v10, 11, v10
	v_lshl_add_u32 v10, v6, 5, v10
	s_add_u32 s12, s12, 0xb34c000
	s_addc_u32 s13, s13, 0
	v_readlane_b32 s24, v255, 7
	s_lshr_b32 s24, s24, 6
	v_readlane_b32 s3, v255, 3
	s_sub_i32 s3, s3, 160
	s_lshl_b32 s3, s3, 3
	s_add_i32 s3, s3, s24
	s_mov_b32 s14, s3
.Lew_loop_b:
	s_cmpk_gt_u32 s3, 0x57f
	s_cbranch_scc1 .Lew_w13_done
	s_lshr_b32 s6, s3, 5
	s_and_b32 s7, s3, 31
	s_lshr_b32 s15, s6, 1
	s_and_b32 s6, s6, 1
	s_lshl_b32 s26, s15, 9
	s_lshl_b32 s27, s6, 8
	s_add_i32 s26, s26, s27
	s_mul_i32 s27, s7, 0x58000
	s_add_i32 s22, s26, s27
	s_mov_b32 s23, 0
	s_lshl_b32 s26, s15, 19
	s_lshl_b32 s27, s6, 17
	s_add_i32 s26, s26, s27
	s_lshl_b32 s27, s7, 6
	s_add_i32 s26, s26, s27
	s_add_u32 s30, s12, s26
	s_addc_u32 s31, s13, 0
	v_lshl_add_u64 v[6:7], s[22:23], 0, v[4:5]
	global_load_dwordx4 v[20:23], v[6:7], off
	s_add_u32 s22, s22, 0x2c00
	v_lshl_add_u64 v[8:9], s[22:23], 0, v[4:5]
	global_load_dwordx4 v[24:27], v[8:9], off
	s_add_u32 s22, s22, 0x2c00
	v_lshl_add_u64 v[6:7], s[22:23], 0, v[4:5]
	global_load_dwordx4 v[28:31], v[6:7], off
	s_add_u32 s22, s22, 0x2c00
	v_lshl_add_u64 v[8:9], s[22:23], 0, v[4:5]
	global_load_dwordx4 v[32:35], v[8:9], off
	s_add_u32 s22, s22, 0x2c00
	v_lshl_add_u64 v[6:7], s[22:23], 0, v[4:5]
	global_load_dwordx4 v[36:39], v[6:7], off
	s_add_u32 s22, s22, 0x2c00
	v_lshl_add_u64 v[8:9], s[22:23], 0, v[4:5]
	global_load_dwordx4 v[40:43], v[8:9], off
	s_add_u32 s22, s22, 0x2c00
	v_lshl_add_u64 v[6:7], s[22:23], 0, v[4:5]
	global_load_dwordx4 v[44:47], v[6:7], off
	s_add_u32 s22, s22, 0x2c00
	v_lshl_add_u64 v[8:9], s[22:23], 0, v[4:5]
	global_load_dwordx4 v[48:51], v[8:9], off
	s_add_u32 s22, s22, 0x2c00
	v_lshl_add_u64 v[6:7], s[22:23], 0, v[4:5]
	global_load_dwordx4 v[52:55], v[6:7], off
	s_add_u32 s22, s22, 0x2c00
	v_lshl_add_u64 v[8:9], s[22:23], 0, v[4:5]
	global_load_dwordx4 v[56:59], v[8:9], off
	s_add_u32 s22, s22, 0x2c00
	v_lshl_add_u64 v[6:7], s[22:23], 0, v[4:5]
	global_load_dwordx4 v[60:63], v[6:7], off
	s_add_u32 s22, s22, 0x2c00
	v_lshl_add_u64 v[8:9], s[22:23], 0, v[4:5]
	global_load_dwordx4 v[64:67], v[8:9], off
	s_add_u32 s22, s22, 0x2c00
	v_lshl_add_u64 v[6:7], s[22:23], 0, v[4:5]
	global_load_dwordx4 v[68:71], v[6:7], off
	s_add_u32 s22, s22, 0x2c00
	v_lshl_add_u64 v[8:9], s[22:23], 0, v[4:5]
	global_load_dwordx4 v[72:75], v[8:9], off
	s_add_u32 s22, s22, 0x2c00
	v_lshl_add_u64 v[6:7], s[22:23], 0, v[4:5]
	global_load_dwordx4 v[76:79], v[6:7], off
	s_add_u32 s22, s22, 0x2c00
	v_lshl_add_u64 v[8:9], s[22:23], 0, v[4:5]
	global_load_dwordx4 v[80:83], v[8:9], off
	s_add_u32 s22, s22, 0x2c00
	s_waitcnt vmcnt(0)
	v_cvt_pk_bf16_f32 v84, v20, v24
	v_cvt_pk_bf16_f32 v85, v28, v32
	v_cvt_pk_bf16_f32 v86, v36, v40
	v_cvt_pk_bf16_f32 v87, v44, v48
	v_cvt_pk_bf16_f32 v88, v52, v56
	v_cvt_pk_bf16_f32 v89, v60, v64
	v_cvt_pk_bf16_f32 v90, v68, v72
	v_cvt_pk_bf16_f32 v91, v76, v80
	v_cvt_pk_bf16_f32 v92, v21, v25
	v_cvt_pk_bf16_f32 v93, v29, v33
	v_cvt_pk_bf16_f32 v94, v37, v41
	v_cvt_pk_bf16_f32 v95, v45, v49
	v_cvt_pk_bf16_f32 v96, v53, v57
	v_cvt_pk_bf16_f32 v97, v61, v65
	v_cvt_pk_bf16_f32 v98, v69, v73
	v_cvt_pk_bf16_f32 v99, v77, v81
	v_cvt_pk_bf16_f32 v100, v22, v26
	v_cvt_pk_bf16_f32 v101, v30, v34
	v_cvt_pk_bf16_f32 v102, v38, v42
	v_cvt_pk_bf16_f32 v103, v46, v50
	v_cvt_pk_bf16_f32 v104, v54, v58
	v_cvt_pk_bf16_f32 v105, v62, v66
	v_cvt_pk_bf16_f32 v106, v70, v74
	v_cvt_pk_bf16_f32 v107, v78, v82
	v_cvt_pk_bf16_f32 v108, v23, v27
	v_cvt_pk_bf16_f32 v109, v31, v35
	v_cvt_pk_bf16_f32 v110, v39, v43
	v_cvt_pk_bf16_f32 v111, v47, v51
	v_cvt_pk_bf16_f32 v112, v55, v59
	v_cvt_pk_bf16_f32 v113, v63, v67
	v_cvt_pk_bf16_f32 v114, v71, v75
	v_cvt_pk_bf16_f32 v115, v79, v83
	global_store_dwordx4 v10, v[84:87], s[30:31] offset:-4096
	global_store_dwordx4 v10, v[88:91], s[30:31] offset:-4080
	global_store_dwordx4 v10, v[92:95], s[30:31] offset:-2048
	global_store_dwordx4 v10, v[96:99], s[30:31] offset:-2032
	global_store_dwordx4 v10, v[100:103], s[30:31]
	global_store_dwordx4 v10, v[104:107], s[30:31] offset:16
	global_store_dwordx4 v10, v[108:111], s[30:31] offset:2048
	global_store_dwordx4 v10, v[112:115], s[30:31] offset:2064
	s_addk_i32 s3, 0x300
	s_branch .Lew_loop_b
; __device__ __forceinline__ unsigned pk_bf16(float lo, float hi) { unsigned r; asm volatile("v_cvt_pk_bf16_f32 %0, %1, %2" : "=v"(r) : "v"(lo), "v"(hi)); return r; }
; #define WT_LOAD() do { _Pragma("unroll") for (int i = 0; i < 16; ++i) rg[i] = sp ? sp[(size_t)(k0 + kq + i * 8) * ld] : 0.f; } while (0)
; __device__ __forceinline__ void phase_weights(int wv, const Params& p, int l, LAS unsigned char* lds, int first, int stride) {
;     ...
;     if (ti < 1536) { WT_DECODE(ti); WT_LOAD(); }
;     while (ti < 1536) {
;         bf16_t* cdst = dst + (size_t)n0 * K + k0; const int cK = K;
;         __syncthreads();
; #pragma unroll
;         for (int i = 0; i < 16; ++i) tile[(kq + i * 8) * 65 + nl] = rg[i];
;         ti += stride;
;         if (ti < 1536) { WT_DECODE(ti); WT_LOAD(); }
;         __syncthreads();
;         { const int nn = tid >> 3, ks = tid & 7; float v[16];
; #pragma unroll
;             for (int j = 0; j < 16; ++j) v[j] = tile[(ks * 16 + j) * 65 + nn];
;             u32x4 w0, w1; w0.x = pk_bf16(v[0], v[1]); w0.y = pk_bf16(v[2], v[3]); w0.z = pk_bf16(v[4], v[5]); w0.w = pk_bf16(v[6], v[7]);
;             w1.x = pk_bf16(v[8], v[9]); w1.y = pk_bf16(v[10], v[11]); w1.z = pk_bf16(v[12], v[13]); w1.w = pk_bf16(v[14], v[15]);
;             bf16_t* o = cdst + (size_t)nn * cK + ks * 16; *(u32x4*)o = w0; *(u32x4*)(o + 8) = w1; }
.Lew_w13_done:
	s_cmpk_lt_u32 s14, 0x280
	s_cbranch_scc1 .Lew_end_b
	s_sub_i32 s3, s14, 0x280
	s_load_dwordx2 s[8:9], s[90:91], 0x80
	v_lshrrev_b32_e32 v6, 4, v2
	v_lshlrev_b32_e32 v12, 4, v3
	v_lshl_add_u32 v12, v6, 16, v12
	v_add_u32_e32 v12, 0x400000, v12
	v_mov_b32_e32 v13, 0
	v_lshlrev_b32_e32 v10, 13, v3
	v_lshl_add_u32 v10, v6, 5, v10
	v_add_u32_e32 v10, 0x1000, v10
	s_waitcnt lgkmcnt(0)
	v_mov_b32_e32 v4, s8
	v_mov_b32_e32 v5, s9
	v_lshl_add_u64 v[4:5], v[4:5], 0, v[12:13]
	s_add_u32 s12, s12, 0xb00000
	s_addc_u32 s13, s13, 0
.Lew_loop_c:
	s_cmpk_gt_u32 s3, 0xff
	s_cbranch_scc1 .Lew_end_b
	s_lshr_b32 s6, s3, 4
	s_and_b32 s7, s3, 15
	s_lshl_b32 s22, s7, 18
	s_lshl_b32 s26, s6, 8
	s_add_i32 s22, s22, s26
	s_mov_b32 s23, 0
	s_lshl_b32 s26, s6, 17
	s_lshl_b32 s27, s7, 7
	s_add_i32 s26, s26, s27
	s_add_u32 s30, s12, s26
	s_addc_u32 s31, s13, 0
	v_lshl_add_u64 v[6:7], s[22:23], 0, v[4:5]
	global_load_dwordx4 v[20:23], v[6:7], off
	s_add_u32 s22, s22, 0x1000
	v_lshl_add_u64 v[8:9], s[22:23], 0, v[4:5]
	global_load_dwordx4 v[24:27], v[8:9], off
	s_add_u32 s22, s22, 0x1000
	v_lshl_add_u64 v[6:7], s[22:23], 0, v[4:5]
	global_load_dwordx4 v[28:31], v[6:7], off
	s_add_u32 s22, s22, 0x1000
	v_lshl_add_u64 v[8:9], s[22:23], 0, v[4:5]
	global_load_dwordx4 v[32:35], v[8:9], off
	s_add_u32 s22, s22, 0x1000
	v_lshl_add_u64 v[6:7], s[22:23], 0, v[4:5]
	global_load_dwordx4 v[36:39], v[6:7], off
	s_add_u32 s22, s22, 0x1000
	v_lshl_add_u64 v[8:9], s[22:23], 0, v[4:5]
	global_load_dwordx4 v[40:43], v[8:9], off
	s_add_u32 s22, s22, 0x1000
	v_lshl_add_u64 v[6:7], s[22:23], 0, v[4:5]
	global_load_dwordx4 v[44:47], v[6:7], off
	s_add_u32 s22, s22, 0x1000
	v_lshl_add_u64 v[8:9], s[22:23], 0, v[4:5]
	global_load_dwordx4 v[48:51], v[8:9], off
	s_add_u32 s22, s22, 0x1000
	v_lshl_add_u64 v[6:7], s[22:23], 0, v[4:5]
	global_load_dwordx4 v[52:55], v[6:7], off
	s_add_u32 s22, s22, 0x1000
	v_lshl_add_u64 v[8:9], s[22:23], 0, v[4:5]
	global_load_dwordx4 v[56:59], v[8:9], off
	s_add_u32 s22, s22, 0x1000
	v_lshl_add_u64 v[6:7], s[22:23], 0, v[4:5]
	global_load_dwordx4 v[60:63], v[6:7], off
	s_add_u32 s22, s22, 0x1000
	v_lshl_add_u64 v[8:9], s[22:23], 0, v[4:5]
	global_load_dwordx4 v[64:67], v[8:9], off
	s_add_u32 s22, s22, 0x1000
	v_lshl_add_u64 v[6:7], s[22:23], 0, v[4:5]
	global_load_dwordx4 v[68:71], v[6:7], off
	s_add_u32 s22, s22, 0x1000
	v_lshl_add_u64 v[8:9], s[22:23], 0, v[4:5]
	global_load_dwordx4 v[72:75], v[8:9], off
	s_add_u32 s22, s22, 0x1000
	v_lshl_add_u64 v[6:7], s[22:23], 0, v[4:5]
	global_load_dwordx4 v[76:79], v[6:7], off
	s_add_u32 s22, s22, 0x1000
	v_lshl_add_u64 v[8:9], s[22:23], 0, v[4:5]
	global_load_dwordx4 v[80:83], v[8:9], off
	s_add_u32 s22, s22, 0x1000
	s_waitcnt vmcnt(0)
	v_cvt_pk_bf16_f32 v84, v20, v24
	v_cvt_pk_bf16_f32 v85, v28, v32
	v_cvt_pk_bf16_f32 v86, v36, v40
	v_cvt_pk_bf16_f32 v87, v44, v48
	v_cvt_pk_bf16_f32 v88, v52, v56
	v_cvt_pk_bf16_f32 v89, v60, v64
	v_cvt_pk_bf16_f32 v90, v68, v72
	v_cvt_pk_bf16_f32 v91, v76, v80
	v_cvt_pk_bf16_f32 v92, v21, v25
	v_cvt_pk_bf16_f32 v93, v29, v33
	v_cvt_pk_bf16_f32 v94, v37, v41
	v_cvt_pk_bf16_f32 v95, v45, v49
	v_cvt_pk_bf16_f32 v96, v53, v57
	v_cvt_pk_bf16_f32 v97, v61, v65
	v_cvt_pk_bf16_f32 v98, v69, v73
	v_cvt_pk_bf16_f32 v99, v77, v81
	v_cvt_pk_bf16_f32 v100, v22, v26
	v_cvt_pk_bf16_f32 v101, v30, v34
	v_cvt_pk_bf16_f32 v102, v38, v42
	v_cvt_pk_bf16_f32 v103, v46, v50
	v_cvt_pk_bf16_f32 v104, v54, v58
	v_cvt_pk_bf16_f32 v105, v62, v66
	v_cvt_pk_bf16_f32 v106, v70, v74
	v_cvt_pk_bf16_f32 v107, v78, v82
	v_cvt_pk_bf16_f32 v108, v23, v27
	v_cvt_pk_bf16_f32 v109, v31, v35
	v_cvt_pk_bf16_f32 v110, v39, v43
	v_cvt_pk_bf16_f32 v111, v47, v51
	v_cvt_pk_bf16_f32 v112, v55, v59
	v_cvt_pk_bf16_f32 v113, v63, v67
	v_cvt_pk_bf16_f32 v114, v71, v75
	v_cvt_pk_bf16_f32 v115, v79, v83
	global_store_dwordx4 v10, v[84:87], s[30:31] offset:-4096
	global_store_dwordx4 v10, v[88:91], s[30:31] offset:-4080
	global_store_dwordx4 v10, v[92:95], s[30:31] offset:-2048
	global_store_dwordx4 v10, v[96:99], s[30:31] offset:-2032
	global_store_dwordx4 v10, v[100:103], s[30:31]
	global_store_dwordx4 v10, v[104:107], s[30:31] offset:16
	global_store_dwordx4 v10, v[108:111], s[30:31] offset:2048
	global_store_dwordx4 v10, v[112:115], s[30:31] offset:2064
	s_addk_i32 s3, 0x80
	s_branch .Lew_loop_c
